# combined: SSM part-E pipelined reads + counted vmcnt, in-proj last-iteration epilogue fold, conversion-loop early reload, 4-wait K-loops
# baseline (speedup 1.0000x reference)
; #define PG8_STAGE(bufoff, gbase, voff) do { _Pragma("unroll") for (int _i = 0; _i < 2; ++_i) \
;         __builtin_amdgcn_global_load_lds((const unsigned*)((const char*)(gbase) + (voff)[_i]), (LAS unsigned*)(lds + (bufoff) + ldsw + _i * 8192), 16, 0, 0); } while (0)
; #define PG8_LDA(dst, b, h) do { _Pragma("unroll") for (int m = 0; m < 4; ++m) _Pragma("unroll") for (int k = 0; k < 2; ++k) dst[m][k] = *(const LAS bf16x8*)(lds + PG8_SA(b, h) + aoff + m * 2048 + k * 1024); } while (0)
; #define PG8_LDB(dst, b, h) do { _Pragma("unroll") for (int n = 0; n < 2; ++n) _Pragma("unroll") for (int k = 0; k < 2; ++k) dst[n][k] = *(const LAS bf16x8*)(lds + PG8_SB(b, h) + boff + n * 2048 + k * 1024); } while (0)
; #define PG8_MMA(ai, bj, At, Bt) do { __builtin_amdgcn_s_setprio(1); _Pragma("unroll") for (int m = 0; m < 4; ++m) _Pragma("unroll") for (int n = 0; n < 2; ++n) _Pragma("unroll") for (int k = 0; k < 2; ++k) \
;         acc[ai][bj][m][n] = __builtin_amdgcn_mfma_f32_16x16x32_bf16(Bt[n][k], At[m][k], acc[ai][bj][m][n], 0, 0, 0); __builtin_amdgcn_s_setprio(0); } while (0)
; #define PG8_WAIT_L(n) asm volatile("s_waitcnt lgkmcnt(" #n ")" ::: "memory")
; #define PG8_BAR __builtin_amdgcn_s_barrier()
; #define PG8_SCHED __builtin_amdgcn_sched_barrier(0)
; template <class Epi>
; __device__ __forceinline__ void gemm_phase(LAS unsigned char* lds, const Gemm g, const StaticOrder& S, const Epi& E) {
;     ...
;             PG8_LDB(B0, 0, 0); PG8_SCHED; PG8_LDA(At, 0, 0); PG8_STAGE(PG8_SA(1, 1), a1 + hstepA, voffA);
;             PG8_WAIT_L(8); PG8_BAR; PG8_WAIT_L(0); PG8_MMA(0, 0, At, B0); PG8_BAR; PG8_SCHED;
;             PG8_LDB(B1, 0, 1); PG8_STAGE(PG8_SB(0, 0), b2, voffB);
;             PG8_BAR; PG8_WAIT_L(0); PG8_MMA(0, 1, At, B1); PG8_BAR;
;             PG8_LDA(At, 0, 1); PG8_STAGE(PG8_SA(0, 0), a2, voffA);
;             PG8_BAR; PG8_WAIT_L(0); PG8_MMA(1, 0, At, B0); PG8_BAR; PG8_SCHED;
.LBB0_158:
	s_add_u32 s42, s38, 0x100
	s_addc_u32 s43, s39, 0
	s_add_i32 s60, 0, 0x10000
	v_add_u32_e32 v0, s60, v152
	ds_read_b128 v[146:149], v0
	ds_read_b128 v[162:165], v0 offset:1024
	ds_read_b128 v[166:169], v0 offset:2048
	ds_read_b128 v[170:173], v0 offset:3072
	s_cmp_eq_u32 s59, 28
	s_cselect_b32 s25, s23, s43
	s_cselect_b32 s24, s55, s42
	s_cselect_b32 s5, s21, s58
	s_cselect_b32 s4, s56, s57
	v_lshl_add_u64 v[150:151], s[38:39], 0, v[140:141]
	s_add_i32 m0, s46, 0xc000
	ds_read_b128 v[174:177], v154
	ds_read_b128 v[188:191], v154 offset:1024
	ds_read_b128 v[192:195], v154 offset:2048
	ds_read_b128 v[196:199], v154 offset:3072
	ds_read_b128 v[200:203], v154 offset:4096
	ds_read_b128 v[204:207], v154 offset:5120
	ds_read_b128 v[208:211], v154 offset:6144
	ds_read_b128 v[212:215], v154 offset:7168
	global_load_lds_dwordx4 v[150:151], off
	v_lshl_add_u64 v[150:151], s[38:39], 0, v[142:143]
	s_add_i32 m0, s46, 0xe000
	s_nop 0
	global_load_lds_dwordx4 v[150:151], off
	s_waitcnt lgkmcnt(8)
	s_barrier
	s_waitcnt lgkmcnt(0)
	s_setprio 1
	s_waitcnt lgkmcnt(0)
	v_mfma_f32_16x16x32_bf16 v[126:129], v[146:149], v[174:177], v[126:129]
	v_mfma_f32_16x16x32_bf16 v[122:125], v[166:169], v[174:177], v[122:125]
	v_mfma_f32_16x16x32_bf16 v[110:113], v[146:149], v[192:195], v[110:113]
	v_mfma_f32_16x16x32_bf16 v[106:109], v[166:169], v[192:195], v[106:109]
	v_mfma_f32_16x16x32_bf16 v[94:97], v[146:149], v[200:203], v[94:97]
	v_mfma_f32_16x16x32_bf16 v[90:93], v[166:169], v[200:203], v[90:93]
	v_mfma_f32_16x16x32_bf16 v[78:81], v[146:149], v[208:211], v[78:81]
	v_mfma_f32_16x16x32_bf16 v[74:77], v[166:169], v[208:211], v[74:77]
	v_mfma_f32_16x16x32_bf16 v[126:129], v[162:165], v[188:191], v[126:129]
	v_mfma_f32_16x16x32_bf16 v[122:125], v[170:173], v[188:191], v[122:125]
	v_mfma_f32_16x16x32_bf16 v[110:113], v[162:165], v[196:199], v[110:113]
	v_mfma_f32_16x16x32_bf16 v[106:109], v[170:173], v[196:199], v[106:109]
	v_mfma_f32_16x16x32_bf16 v[94:97], v[162:165], v[204:207], v[94:97]
	v_mfma_f32_16x16x32_bf16 v[90:93], v[170:173], v[204:207], v[90:93]
	v_mfma_f32_16x16x32_bf16 v[78:81], v[162:165], v[212:215], v[78:81]
	v_mfma_f32_16x16x32_bf16 v[74:77], v[170:173], v[212:215], v[74:77]
	s_setprio 0
	s_barrier
	s_add_i32 s61, 0, 0x14000
	s_add_i32 s38, s60, s45
	v_add_u32_e32 v0, s61, v152
	v_lshl_add_u64 v[150:151], s[4:5], 0, v[134:135]
	s_mov_b32 m0, s38
	ds_read_b128 v[216:219], v0
	ds_read_b128 v[220:223], v0 offset:1024
	ds_read_b128 v[224:227], v0 offset:2048
	ds_read_b128 v[228:231], v0 offset:3072
	global_load_lds_dwordx4 v[150:151], off
	v_lshl_add_u64 v[184:185], s[4:5], 0, v[130:131]
	s_add_i32 m0, s38, 0x2000
	s_nop 0
	global_load_lds_dwordx4 v[184:185], off
	s_waitcnt vmcnt(10)
	s_barrier
	s_waitcnt lgkmcnt(0)
	s_setprio 1
	s_waitcnt lgkmcnt(0)
	v_mfma_f32_16x16x32_bf16 v[118:121], v[216:219], v[174:177], v[118:121]
	v_mfma_f32_16x16x32_bf16 v[114:117], v[224:227], v[174:177], v[114:117]
	v_mfma_f32_16x16x32_bf16 v[102:105], v[216:219], v[192:195], v[102:105]
	v_mfma_f32_16x16x32_bf16 v[98:101], v[224:227], v[192:195], v[98:101]
	v_mfma_f32_16x16x32_bf16 v[86:89], v[216:219], v[200:203], v[86:89]
	v_mfma_f32_16x16x32_bf16 v[82:85], v[224:227], v[200:203], v[82:85]
	v_mfma_f32_16x16x32_bf16 v[70:73], v[216:219], v[208:211], v[70:73]
	v_mfma_f32_16x16x32_bf16 v[66:69], v[224:227], v[208:211], v[66:69]
	v_mfma_f32_16x16x32_bf16 v[118:121], v[220:223], v[188:191], v[118:121]
	v_mfma_f32_16x16x32_bf16 v[114:117], v[228:231], v[188:191], v[114:117]
	v_mfma_f32_16x16x32_bf16 v[102:105], v[220:223], v[196:199], v[102:105]
	v_mfma_f32_16x16x32_bf16 v[98:101], v[228:231], v[196:199], v[98:101]
	v_mfma_f32_16x16x32_bf16 v[86:89], v[220:223], v[204:207], v[86:89]
	v_mfma_f32_16x16x32_bf16 v[82:85], v[228:231], v[204:207], v[82:85]
	v_mfma_f32_16x16x32_bf16 v[70:73], v[220:223], v[212:215], v[70:73]
	v_mfma_f32_16x16x32_bf16 v[66:69], v[228:231], v[212:215], v[66:69]
	s_setprio 0
	s_mov_b32 m0, s46
	v_lshl_add_u64 v[186:187], s[24:25], 0, v[136:137]
	s_barrier
	ds_read_b128 v[174:177], v154 offset:16384
	ds_read_b128 v[188:191], v154 offset:17408
	ds_read_b128 v[192:195], v154 offset:18432
	ds_read_b128 v[196:199], v154 offset:19456
	ds_read_b128 v[200:203], v154 offset:20480
	ds_read_b128 v[204:207], v154 offset:21504
	ds_read_b128 v[208:211], v154 offset:22528
	ds_read_b128 v[212:215], v154 offset:23552
	global_load_lds_dwordx4 v[186:187], off
	v_lshl_add_u64 v[244:245], s[24:25], 0, v[132:133]
	s_mov_b32 m0, s47
	s_nop 0
	global_load_lds_dwordx4 v[244:245], off
	s_barrier
	s_waitcnt lgkmcnt(0)
	s_setprio 1
	s_waitcnt lgkmcnt(0)
	v_mfma_f32_16x16x32_bf16 v[62:65], v[146:149], v[174:177], v[62:65]
	v_mfma_f32_16x16x32_bf16 v[58:61], v[166:169], v[174:177], v[58:61]
	v_mfma_f32_16x16x32_bf16 v[46:49], v[146:149], v[192:195], v[46:49]
	v_mfma_f32_16x16x32_bf16 v[42:45], v[166:169], v[192:195], v[42:45]
	v_mfma_f32_16x16x32_bf16 v[30:33], v[146:149], v[200:203], v[30:33]
	v_mfma_f32_16x16x32_bf16 v[26:29], v[166:169], v[200:203], v[26:29]
	v_mfma_f32_16x16x32_bf16 v[14:17], v[146:149], v[208:211], v[14:17]
	v_mfma_f32_16x16x32_bf16 v[10:13], v[166:169], v[208:211], v[10:13]
	v_mfma_f32_16x16x32_bf16 v[62:65], v[162:165], v[188:191], v[62:65]
	v_mfma_f32_16x16x32_bf16 v[58:61], v[170:173], v[188:191], v[58:61]
	v_mfma_f32_16x16x32_bf16 v[46:49], v[162:165], v[196:199], v[46:49]
	v_mfma_f32_16x16x32_bf16 v[42:45], v[170:173], v[196:199], v[42:45]
	v_mfma_f32_16x16x32_bf16 v[30:33], v[162:165], v[204:207], v[30:33]
	v_mfma_f32_16x16x32_bf16 v[26:29], v[170:173], v[204:207], v[26:29]
	v_mfma_f32_16x16x32_bf16 v[14:17], v[162:165], v[212:215], v[14:17]
	v_mfma_f32_16x16x32_bf16 v[10:13], v[170:173], v[212:215], v[10:13]
	s_setprio 0
	s_barrier
; #define PG8_STAGE(bufoff, gbase, voff) do { _Pragma("unroll") for (int _i = 0; _i < 2; ++_i) \
;         __builtin_amdgcn_global_load_lds((const unsigned*)((const char*)(gbase) + (voff)[_i]), (LAS unsigned*)(lds + (bufoff) + ldsw + _i * 8192), 16, 0, 0); } while (0)
; #define PG8_LDA(dst, b, h) do { _Pragma("unroll") for (int m = 0; m < 4; ++m) _Pragma("unroll") for (int k = 0; k < 2; ++k) dst[m][k] = *(const LAS bf16x8*)(lds + PG8_SA(b, h) + aoff + m * 2048 + k * 1024); } while (0)
; #define PG8_LDB(dst, b, h) do { _Pragma("unroll") for (int n = 0; n < 2; ++n) _Pragma("unroll") for (int k = 0; k < 2; ++k) dst[n][k] = *(const LAS bf16x8*)(lds + PG8_SB(b, h) + boff + n * 2048 + k * 1024); } while (0)
; #define PG8_MMA(ai, bj, At, Bt) do { __builtin_amdgcn_s_setprio(1); _Pragma("unroll") for (int m = 0; m < 4; ++m) _Pragma("unroll") for (int n = 0; n < 2; ++n) _Pragma("unroll") for (int k = 0; k < 2; ++k) \
;         acc[ai][bj][m][n] = __builtin_amdgcn_mfma_f32_16x16x32_bf16(Bt[n][k], At[m][k], acc[ai][bj][m][n], 0, 0, 0); __builtin_amdgcn_s_setprio(0); } while (0)
; #define PG8_WAIT_V(n) asm volatile("s_waitcnt vmcnt(" #n ")" ::: "memory")
; #define PG8_WAIT_L(n) asm volatile("s_waitcnt lgkmcnt(" #n ")" ::: "memory")
; #define PG8_BAR __builtin_amdgcn_s_barrier()
; #define PG8_SCHED __builtin_amdgcn_sched_barrier(0)
; template <class Epi>
; __device__ __forceinline__ void gemm_phase(LAS unsigned char* lds, const Gemm g, const StaticOrder& S, const Epi& E) {
;     ...
;             PG8_STAGE(PG8_SB(0, 1), b2 + hstepB, voffB);
;             PG8_WAIT_V(6); PG8_BAR; PG8_MMA(1, 1, At, B1); PG8_BAR;
;             PG8_LDB(B0, 1, 0); PG8_SCHED; PG8_LDA(At, 1, 0); PG8_STAGE(PG8_SA(0, 1), a2 + hstepA, voffA);
;             PG8_WAIT_L(8); PG8_BAR; PG8_WAIT_L(0); PG8_MMA(0, 0, At, B0); PG8_BAR; PG8_SCHED;
;             PG8_LDB(B1, 1, 1); PG8_STAGE(PG8_SB(1, 0), b3, voffB);
	s_add_u32 s38, s4, 0x80000
	s_addc_u32 s39, s5, 0
	s_add_i32 s60, s61, s45
	v_lshl_add_u64 v[146:147], s[38:39], 0, v[134:135]
	s_mov_b32 m0, s60
	s_nop 0
	global_load_lds_dwordx4 v[146:147], off
	v_lshl_add_u64 v[146:147], s[38:39], 0, v[130:131]
	s_add_i32 m0, s60, 0x2000
	s_nop 0
	global_load_lds_dwordx4 v[146:147], off
	s_waitcnt vmcnt(8)
	s_barrier
	s_setprio 1
	v_mfma_f32_16x16x32_bf16 v[54:57], v[216:219], v[174:177], v[54:57]
	v_mfma_f32_16x16x32_bf16 v[50:53], v[224:227], v[174:177], v[50:53]
	v_mfma_f32_16x16x32_bf16 v[38:41], v[216:219], v[192:195], v[38:41]
	v_mfma_f32_16x16x32_bf16 v[34:37], v[224:227], v[192:195], v[34:37]
	v_mfma_f32_16x16x32_bf16 v[22:25], v[216:219], v[200:203], v[22:25]
	v_mfma_f32_16x16x32_bf16 v[18:21], v[224:227], v[200:203], v[18:21]
	v_mfma_f32_16x16x32_bf16 v[6:9], v[216:219], v[208:211], v[6:9]
	v_mfma_f32_16x16x32_bf16 v[2:5], v[224:227], v[208:211], v[2:5]
	v_mfma_f32_16x16x32_bf16 v[54:57], v[220:223], v[188:191], v[54:57]
	v_mfma_f32_16x16x32_bf16 v[50:53], v[228:231], v[188:191], v[50:53]
	v_mfma_f32_16x16x32_bf16 v[38:41], v[220:223], v[196:199], v[38:41]
	v_mfma_f32_16x16x32_bf16 v[34:37], v[228:231], v[196:199], v[34:37]
	v_mfma_f32_16x16x32_bf16 v[22:25], v[220:223], v[204:207], v[22:25]
	v_mfma_f32_16x16x32_bf16 v[18:21], v[228:231], v[204:207], v[18:21]
	v_mfma_f32_16x16x32_bf16 v[6:9], v[220:223], v[212:215], v[6:9]
	v_mfma_f32_16x16x32_bf16 v[2:5], v[228:231], v[212:215], v[2:5]
	s_setprio 0
	s_add_i32 s38, 0, 0x18000
	v_add_u32_e32 v0, s38, v152
	s_barrier
	ds_read_b128 v[146:149], v0
	ds_read_b128 v[162:165], v0 offset:1024
	ds_read_b128 v[166:169], v0 offset:2048
	ds_read_b128 v[170:173], v0 offset:3072
	s_add_u32 s24, s24, 0x80000
	s_addc_u32 s25, s25, 0
	s_mov_b32 m0, s48
	v_lshl_add_u64 v[216:217], s[24:25], 0, v[136:137]
	ds_read_b128 v[174:177], v154 offset:32768
	ds_read_b128 v[188:191], v154 offset:33792
	ds_read_b128 v[192:195], v154 offset:34816
	ds_read_b128 v[196:199], v154 offset:35840
	ds_read_b128 v[200:203], v154 offset:36864
	ds_read_b128 v[204:207], v154 offset:37888
	ds_read_b128 v[208:211], v154 offset:38912
	ds_read_b128 v[212:215], v154 offset:39936
	global_load_lds_dwordx4 v[216:217], off
	v_lshl_add_u64 v[216:217], s[24:25], 0, v[132:133]
	s_mov_b32 m0, s49
	s_nop 0
	global_load_lds_dwordx4 v[216:217], off
	s_waitcnt lgkmcnt(8)
	s_barrier
	s_waitcnt lgkmcnt(0)
	s_setprio 1
	s_waitcnt lgkmcnt(0)
	v_mfma_f32_16x16x32_bf16 v[126:129], v[146:149], v[174:177], v[126:129]
	v_mfma_f32_16x16x32_bf16 v[122:125], v[166:169], v[174:177], v[122:125]
	v_mfma_f32_16x16x32_bf16 v[110:113], v[146:149], v[192:195], v[110:113]
	v_mfma_f32_16x16x32_bf16 v[106:109], v[166:169], v[192:195], v[106:109]
	v_mfma_f32_16x16x32_bf16 v[94:97], v[146:149], v[200:203], v[94:97]
	v_mfma_f32_16x16x32_bf16 v[90:93], v[166:169], v[200:203], v[90:93]
	v_mfma_f32_16x16x32_bf16 v[78:81], v[146:149], v[208:211], v[78:81]
	v_mfma_f32_16x16x32_bf16 v[74:77], v[166:169], v[208:211], v[74:77]
	v_mfma_f32_16x16x32_bf16 v[126:129], v[162:165], v[188:191], v[126:129]
	v_mfma_f32_16x16x32_bf16 v[122:125], v[170:173], v[188:191], v[122:125]
	v_mfma_f32_16x16x32_bf16 v[110:113], v[162:165], v[196:199], v[110:113]
	v_mfma_f32_16x16x32_bf16 v[106:109], v[170:173], v[196:199], v[106:109]
	v_mfma_f32_16x16x32_bf16 v[94:97], v[162:165], v[204:207], v[94:97]
	v_mfma_f32_16x16x32_bf16 v[90:93], v[170:173], v[204:207], v[90:93]
	v_mfma_f32_16x16x32_bf16 v[78:81], v[162:165], v[212:215], v[78:81]
	v_mfma_f32_16x16x32_bf16 v[74:77], v[170:173], v[212:215], v[74:77]
	s_setprio 0
	s_barrier
	s_add_i32 s24, 0, 0x1c000
	s_add_i32 s25, s38, s45
	v_add_u32_e32 v0, s24, v152
	v_lshl_add_u64 v[150:151], v[150:151], 0, s[6:7]
	s_mov_b32 m0, s25
	ds_read_b128 v[216:219], v0
	ds_read_b128 v[220:223], v0 offset:1024
	ds_read_b128 v[224:227], v0 offset:2048
	ds_read_b128 v[228:231], v0 offset:3072
	global_load_lds_dwordx4 v[150:151], off
	v_lshl_add_u64 v[150:151], v[184:185], 0, s[6:7]
	s_add_i32 m0, s25, 0x2000
	s_nop 0
	global_load_lds_dwordx4 v[150:151], off
	s_waitcnt vmcnt(10)
	s_barrier
; __device__ __forceinline__ unsigned cvt_pk_bf16(float lo, float hi) { unsigned r; asm volatile("v_cvt_pk_bf16_f32 %0, %1, %2" : "=v"(r) : "v"(lo), "v"(hi)); return r; }
; #define PG8_STAGE(bufoff, gbase, voff) do { _Pragma("unroll") for (int _i = 0; _i < 2; ++_i) \
;         __builtin_amdgcn_global_load_lds((const unsigned*)((const char*)(gbase) + (voff)[_i]), (LAS unsigned*)(lds + (bufoff) + ldsw + _i * 8192), 16, 0, 0); } while (0)
; #define PG8_LDA(dst, b, h) do { _Pragma("unroll") for (int m = 0; m < 4; ++m) _Pragma("unroll") for (int k = 0; k < 2; ++k) dst[m][k] = *(const LAS bf16x8*)(lds + PG8_SA(b, h) + aoff + m * 2048 + k * 1024); } while (0)
; #define PG8_WAIT_V(n) asm volatile("s_waitcnt vmcnt(" #n ")" ::: "memory")
; #define PG8_WAIT_L(n) asm volatile("s_waitcnt lgkmcnt(" #n ")" ::: "memory")
; template <class Epi>
; __device__ __forceinline__ void gemm_phase(LAS unsigned char* lds, const Gemm g, const StaticOrder& S, const Epi& E) {
;     ...
;             PG8_LDB(B1, 1, 1); PG8_STAGE(PG8_SB(1, 0), b3, voffB);
;             PG8_BAR; PG8_WAIT_L(0); PG8_MMA(0, 1, At, B1); PG8_BAR;
;             PG8_LDA(At, 1, 1); PG8_STAGE(PG8_SA(1, 0), a3, voffA);
;             PG8_BAR; PG8_WAIT_L(0); PG8_MMA(1, 0, At, B0); PG8_BAR; PG8_SCHED;
;             PG8_STAGE(PG8_SB(1, 1), b3 + hstepB, voffB);
;             PG8_WAIT_V(6); PG8_BAR; PG8_MMA(1, 1, At, B1); PG8_BAR;
;     __device__ __forceinline__ void operator()(const f32x4 (&acc)[2][2][4][2], const Unit& u, int wr, int wc, int fr, int fq, const Pre& pp) const {
;         const int row0 = u.pm * BM + wr * 64 + fr, col0 = u.pn * BM + wc * 32 + 8 * fq;
;         const bool gm = (UG != nullptr) && (u.pn < DE / BM);
;         const float (&rs)[8] = pp.rs;
; #pragma unroll
;         for (int ai = 0; ai < 2; ++ai)
; #pragma unroll
;             for (int m = 0; m < 4; ++m) { const int r = row0 + ai * HALF + m * 16; const float inv = rsqrtf(rs[ai * 4 + m] * (1.0f / DM) + EPS);
; #pragma unroll
;                 for (int bj = 0; bj < 2; ++bj) { const f32x4 v0 = acc[ai][bj][m][0] * inv, v1 = acc[ai][bj][m][1] * inv; const int c = col0 + bj * HALF;
;                     u32x4 w; w.x = cvt_pk_bf16(v0[0], v0[1]); w.y = cvt_pk_bf16(v0[2], v0[3]); w.z = cvt_pk_bf16(v1[0], v1[1]); w.w = cvt_pk_bf16(v1[2], v1[3]);
;                     bf16_t* dst = gm ? UG + (size_t)(c >> 4) * GSTR + r * 16 + (c & 15) : O + (size_t)r * DE2 + c;
	s_waitcnt lgkmcnt(0)
	s_setprio 1
	s_waitcnt lgkmcnt(0)
	v_mfma_f32_16x16x32_bf16 v[118:121], v[216:219], v[174:177], v[118:121]
	v_mfma_f32_16x16x32_bf16 v[114:117], v[224:227], v[174:177], v[114:117]
	v_mfma_f32_16x16x32_bf16 v[102:105], v[216:219], v[192:195], v[102:105]
	v_mfma_f32_16x16x32_bf16 v[98:101], v[224:227], v[192:195], v[98:101]
	v_mfma_f32_16x16x32_bf16 v[86:89], v[216:219], v[200:203], v[86:89]
	v_mfma_f32_16x16x32_bf16 v[82:85], v[224:227], v[200:203], v[82:85]
	v_mfma_f32_16x16x32_bf16 v[70:73], v[216:219], v[208:211], v[70:73]
	v_mfma_f32_16x16x32_bf16 v[66:69], v[224:227], v[208:211], v[66:69]
	v_mfma_f32_16x16x32_bf16 v[118:121], v[220:223], v[188:191], v[118:121]
	v_mfma_f32_16x16x32_bf16 v[114:117], v[228:231], v[188:191], v[114:117]
	v_mfma_f32_16x16x32_bf16 v[102:105], v[220:223], v[196:199], v[102:105]
	v_mfma_f32_16x16x32_bf16 v[98:101], v[228:231], v[196:199], v[98:101]
	v_mfma_f32_16x16x32_bf16 v[86:89], v[220:223], v[204:207], v[86:89]
	v_mfma_f32_16x16x32_bf16 v[82:85], v[228:231], v[204:207], v[82:85]
	v_mfma_f32_16x16x32_bf16 v[70:73], v[220:223], v[212:215], v[70:73]
	v_mfma_f32_16x16x32_bf16 v[66:69], v[228:231], v[212:215], v[66:69]
	s_setprio 0
	s_mov_b32 m0, s50
	v_lshl_add_u64 v[150:151], v[186:187], 0, s[6:7]
	s_barrier
	ds_read_b128 v[174:177], v154 offset:49152
	ds_read_b128 v[188:191], v154 offset:50176
	ds_read_b128 v[192:195], v154 offset:51200
	ds_read_b128 v[196:199], v154 offset:52224
	ds_read_b128 v[200:203], v154 offset:53248
	ds_read_b128 v[204:207], v154 offset:54272
	ds_read_b128 v[208:211], v154 offset:55296
	ds_read_b128 v[212:215], v154 offset:56320
	global_load_lds_dwordx4 v[150:151], off
	v_lshl_add_u64 v[150:151], v[244:245], 0, s[6:7]
	s_mov_b32 m0, s51
	s_nop 0
	global_load_lds_dwordx4 v[150:151], off
	s_barrier
	s_waitcnt lgkmcnt(0)
	s_setprio 1
	s_waitcnt lgkmcnt(0)
	v_mfma_f32_16x16x32_bf16 v[62:65], v[146:149], v[174:177], v[62:65]
	v_mfma_f32_16x16x32_bf16 v[58:61], v[166:169], v[174:177], v[58:61]
	v_mfma_f32_16x16x32_bf16 v[46:49], v[146:149], v[192:195], v[46:49]
	v_mfma_f32_16x16x32_bf16 v[42:45], v[166:169], v[192:195], v[42:45]
	v_mfma_f32_16x16x32_bf16 v[30:33], v[146:149], v[200:203], v[30:33]
	v_mfma_f32_16x16x32_bf16 v[26:29], v[166:169], v[200:203], v[26:29]
	v_mfma_f32_16x16x32_bf16 v[14:17], v[146:149], v[208:211], v[14:17]
	v_mfma_f32_16x16x32_bf16 v[10:13], v[166:169], v[208:211], v[10:13]
	v_mfma_f32_16x16x32_bf16 v[62:65], v[162:165], v[188:191], v[62:65]
	v_mfma_f32_16x16x32_bf16 v[58:61], v[170:173], v[188:191], v[58:61]
	v_mfma_f32_16x16x32_bf16 v[46:49], v[162:165], v[196:199], v[46:49]
	v_mfma_f32_16x16x32_bf16 v[42:45], v[170:173], v[196:199], v[42:45]
	v_mfma_f32_16x16x32_bf16 v[30:33], v[162:165], v[204:207], v[30:33]
	v_mfma_f32_16x16x32_bf16 v[26:29], v[170:173], v[204:207], v[26:29]
	v_mfma_f32_16x16x32_bf16 v[14:17], v[162:165], v[212:215], v[14:17]
	v_mfma_f32_16x16x32_bf16 v[10:13], v[170:173], v[212:215], v[10:13]
	s_setprio 0
	s_barrier
	s_add_u32 s4, s4, 0x80080
	s_addc_u32 s5, s5, 0
	s_add_i32 s24, s24, s45
	v_lshl_add_u64 v[146:147], s[4:5], 0, v[134:135]
	s_mov_b32 m0, s24
	s_nop 0
	global_load_lds_dwordx4 v[146:147], off
	v_lshl_add_u64 v[146:147], s[4:5], 0, v[130:131]
	s_add_i32 m0, s24, 0x2000
	s_nop 0
	global_load_lds_dwordx4 v[146:147], off
	s_waitcnt vmcnt(8)
	s_barrier
	s_setprio 1
	v_mfma_f32_16x16x32_bf16 v[54:57], v[216:219], v[174:177], v[54:57]
	v_mfma_f32_16x16x32_bf16 v[50:53], v[224:227], v[174:177], v[50:53]
	v_mfma_f32_16x16x32_bf16 v[38:41], v[216:219], v[192:195], v[38:41]
	v_mfma_f32_16x16x32_bf16 v[34:37], v[224:227], v[192:195], v[34:37]
	v_mfma_f32_16x16x32_bf16 v[22:25], v[216:219], v[200:203], v[22:25]
	v_mfma_f32_16x16x32_bf16 v[18:21], v[224:227], v[200:203], v[18:21]
	v_mfma_f32_16x16x32_bf16 v[6:9], v[216:219], v[208:211], v[6:9]
	v_mfma_f32_16x16x32_bf16 v[2:5], v[224:227], v[208:211], v[2:5]
	v_mfma_f32_16x16x32_bf16 v[54:57], v[220:223], v[188:191], v[54:57]
	v_mfma_f32_16x16x32_bf16 v[50:53], v[228:231], v[188:191], v[50:53]
	v_mfma_f32_16x16x32_bf16 v[38:41], v[220:223], v[196:199], v[38:41]
	v_mfma_f32_16x16x32_bf16 v[34:37], v[228:231], v[196:199], v[34:37]
	v_mfma_f32_16x16x32_bf16 v[22:25], v[220:223], v[204:207], v[22:25]
	v_mfma_f32_16x16x32_bf16 v[18:21], v[228:231], v[204:207], v[18:21]
	v_mfma_f32_16x16x32_bf16 v[6:9], v[220:223], v[212:215], v[6:9]
	v_mfma_f32_16x16x32_bf16 v[2:5], v[228:231], v[212:215], v[2:5]
	s_setprio 0
	s_add_i32 s59, s59, 2
	s_add_u32 s57, s57, 0x100
	s_addc_u32 s58, s58, 0
	s_cmp_gt_u32 s59, 27
	s_mov_b64 s[38:39], s[42:43]
	s_barrier
	s_cbranch_scc0 .LBB0_158
	v_readlane_b32 s100, v254, 47
	v_lshl_add_u32 v251, s54, 8, v139
	v_lshl_or_b32 v144, s53, 8, v153
	s_cmp_lg_u32 s100, 0
	s_cselect_b32 s100, 1, 0
	s_cmp_lt_i32 s53, 16
	s_cselect_b32 s101, 1, 0
	s_and_b32 s100, s100, s101
	s_cmp_lg_u32 s100, 0
	s_cbranch_scc1 .Lpk_setup_gm
	v_lshlrev_b32_e32 v250, 14, v251
	v_lshl_add_u32 v250, v144, 1, v250
	s_mov_b64 s[100:101], s[16:17]
	s_branch .Lpk_setup_done

; #define LDS_BARRIER() asm volatile("s_waitcnt lgkmcnt(0)\n\ts_barrier" ::: "memory")
; __device__ void phase_ssm(int j, unsigned char* lds) {
;     ...
;             LDS_BARRIER();
; #pragma unroll
;             for (int it = 0; it < 4; ++it) { const int pid = tid + NTHREADS * it, tt = pid >> 1, half = pid & 1;
;                 *(u32x4*)(lds + L_UB + (tt >> 4) * U_PITCH + (tt & 15) * 32 + half * 16) = pf[it]; }
;             if (seg < 7) {
; #pragma unroll
;                 for (int it = 0; it < 4; ++it) pf[it] = *(const u32x4*)(ug + (size_t)(seg + 1) * (SEGC * TCH * 16) + (size_t)(tid + NTHREADS * it) * 8); }
.LBB0_717:
	s_waitcnt lgkmcnt(0)
	s_barrier
	s_cmp_eq_u32 s23, 0
	s_cbranch_scc1 .Lssm_a_first
	s_waitcnt vmcnt(11)
	ds_write_b128 v207, v[18:21]
	s_waitcnt vmcnt(10)
	ds_write_b128 v208, v[22:25]
	s_waitcnt vmcnt(9)
	ds_write_b128 v209, v[26:29]
	s_waitcnt vmcnt(8)
	ds_write_b128 v210, v[30:33]
	s_branch .Lssm_a_join
.Lssm_a_first:
	s_waitcnt vmcnt(3)
	ds_write_b128 v207, v[18:21]
	s_waitcnt vmcnt(2)
	ds_write_b128 v208, v[22:25]
	s_waitcnt vmcnt(1)
	ds_write_b128 v209, v[26:29]
	s_waitcnt vmcnt(0)
	ds_write_b128 v210, v[30:33]
.Lssm_a_join:
	s_cmp_eq_u32 s23, 7
	s_cbranch_scc1 .LBB0_719
	s_lshl_b32 s0, s23, 15
	s_add_u32 s0, s38, s0
	s_addc_u32 s1, s39, 0
	s_add_u32 s0, s0, 0x8000
	s_addc_u32 s1, s1, 0
	v_lshl_add_u64 v[8:9], s[0:1], 0, v[136:137]
	v_lshl_add_u64 v[2:3], s[0:1], 0, v[142:143]
	v_lshl_add_u64 v[4:5], s[0:1], 0, v[140:141]
	v_lshl_add_u64 v[6:7], s[0:1], 0, v[138:139]
	global_load_dwordx4 v[18:21], v[8:9], off
	global_load_dwordx4 v[22:25], v[6:7], off
	global_load_dwordx4 v[26:29], v[4:5], off
	global_load_dwordx4 v[30:33], v[2:3], off
